# v51 + scan: silu(z) of the next super-chunk's tokens 0-31 computed by waves 4-7 under chunks 0,1 of step C (raw window wait moved to the B barrier); waves 0-3 skip the silu block in step A1 after the
# baseline (speedup 1.0000x reference)
.LBB0_542:
	v_cmp_gt_i32_e64 s[22:23], s24, v89
	s_and_saveexec_b64 s[24:25], s[22:23]
	s_cbranch_execz .LBB0_544
	s_cmp_eq_u32 s29, 0
	s_cbranch_scc1 .Lsz_do
	s_andn2_b64 vcc, s[26:27], s[36:37]
	s_cbranch_vccnz .LBB0_544
.Lsz_do:
	ds_read_b128 v[20:23], v143
	ds_read_b128 v[24:27], v145
	ds_read_b128 v[28:31], v225
	s_waitcnt lgkmcnt(1)
	v_sub_f16_e32 v8, v24, v20
	v_sub_f16_sdwa v9, v24, v20 dst_sel:DWORD dst_unused:UNUSED_PAD src0_sel:WORD_1 src1_sel:WORD_1
	v_sub_f16_e32 v11, v25, v21
	v_sub_f16_sdwa v24, v25, v21 dst_sel:DWORD dst_unused:UNUSED_PAD src0_sel:WORD_1 src1_sel:WORD_1
	v_sub_f16_e32 v32, v27, v23
	v_sub_f16_sdwa v27, v27, v23 dst_sel:DWORD dst_unused:UNUSED_PAD src0_sel:WORD_1 src1_sel:WORD_1
	v_sub_f16_e32 v25, v26, v22
	v_sub_f16_sdwa v26, v26, v22 dst_sel:DWORD dst_unused:UNUSED_PAD src0_sel:WORD_1 src1_sel:WORD_1
	v_pack_b32_f16 v27, v32, v27
	v_pack_b32_f16 v11, v11, v24
	s_waitcnt lgkmcnt(0)
	v_pk_fma_f16 v31, v31, v27, v23
	v_pack_b32_f16 v23, v25, v26
	v_pk_fma_f16 v11, v29, v11, v21
	v_pk_fma_f16 v27, v30, v23, v22
	v_fma_mix_f32 v23, v11, s87, 0 op_sel_hi:[1,0,0]
	v_cvt_f32_f16_e32 v22, v11
	v_exp_f32_e32 v24, v23
	v_fma_mix_f32 v23, v11, s87, 0 op_sel:[1,0,0] op_sel_hi:[1,0,0]
	v_pack_b32_f16 v8, v8, v9
	v_exp_f32_e32 v25, v23
	v_cvt_f32_f16_sdwa v23, v11 dst_sel:DWORD dst_unused:UNUSED_PAD src0_sel:WORD_1
	v_add_f32_e32 v11, 1.0, v24
	v_rcp_f32_e32 v24, v11
	v_add_f32_e32 v11, 1.0, v25
	v_rcp_f32_e32 v25, v11
	v_fma_mix_f32 v11, v27, s87, 0 op_sel_hi:[1,0,0]
	v_pk_fma_f16 v9, v28, v8, v20
	v_exp_f32_e32 v11, v11
	v_fma_mix_f32 v28, v27, s87, 0 op_sel:[1,0,0] op_sel_hi:[1,0,0]
	v_fma_mix_f32 v20, v9, s87, 0 op_sel_hi:[1,0,0]
	v_exp_f32_e32 v29, v28
	v_add_f32_e32 v11, 1.0, v11
	v_rcp_f32_e32 v28, v11
	v_fma_mix_f32 v21, v9, s87, 0 op_sel:[1,0,0] op_sel_hi:[1,0,0]
	v_add_f32_e32 v11, 1.0, v29
	v_rcp_f32_e32 v29, v11
	v_fma_mix_f32 v11, v31, s87, 0 op_sel_hi:[1,0,0]
	v_fma_mix_f32 v32, v31, s87, 0 op_sel:[1,0,0] op_sel_hi:[1,0,0]
	v_exp_f32_e32 v11, v11
	v_exp_f32_e32 v20, v20
	v_exp_f32_e32 v21, v21
	v_exp_f32_e32 v33, v32
	v_add_f32_e32 v11, 1.0, v11
	v_add_f32_e32 v20, 1.0, v20
	v_add_f32_e32 v21, 1.0, v21
	v_rcp_f32_e32 v32, v11
	v_add_f32_e32 v11, 1.0, v33
	v_cvt_f32_f16_e32 v8, v9
	v_cvt_f32_f16_sdwa v9, v9 dst_sel:DWORD dst_unused:UNUSED_PAD src0_sel:WORD_1
	v_rcp_f32_e32 v20, v20
	v_rcp_f32_e32 v21, v21
	v_cvt_f32_f16_e32 v26, v27
	v_cvt_f32_f16_sdwa v27, v27 dst_sel:DWORD dst_unused:UNUSED_PAD src0_sel:WORD_1
	v_cvt_f32_f16_e32 v30, v31
	v_cvt_f32_f16_sdwa v31, v31 dst_sel:DWORD dst_unused:UNUSED_PAD src0_sel:WORD_1
	v_rcp_f32_e32 v33, v11
	v_pk_fma_f32 v[8:9], v[8:9], v[20:21], 0 op_sel_hi:[1,1,0]
	v_pk_fma_f32 v[20:21], v[22:23], v[24:25], 0 op_sel_hi:[1,1,0]
	v_pk_fma_f32 v[24:25], v[26:27], v[28:29], 0 op_sel_hi:[1,1,0]
	v_pk_fma_f32 v[22:23], v[30:31], v[32:33], 0 op_sel_hi:[1,1,0]
	v_cvt_pk_f16_f32 v21, v20, v21
	v_cvt_pk_f16_f32 v23, v22, v23
	v_cvt_pk_f16_f32 v22, v24, v25
	v_cvt_pk_f16_f32 v20, v8, v9
	ds_write_b128 v146, v[20:23]

.LBB0_578:
	s_waitcnt vmcnt(0)
	s_cmp_eq_u32 s28, s29
	s_waitcnt lgkmcnt(0)
	s_barrier
	s_cselect_b64 s[24:25], -1, 0
	s_or_b64 s[24:25], s[54:55], s[24:25]
	s_and_b64 vcc, exec, s[24:25]
	s_cbranch_vccnz .Lds_early
	s_min_u32 s24, s33, 64
	s_lshr_b32 s24, s24, 4
	s_max_u32 s24, s24, 1
	v_mov_b32_e32 v42, v125
	v_mov_b32_e32 v43, v130
	v_mov_b32_e32 v82, v129
	v_mov_b32_e32 v83, v128
	v_mov_b32_e32 v84, v105
	v_mov_b32_e32 v85, v127
	v_mov_b32_e32 v86, v126
	s_waitcnt lgkmcnt(0)
	s_setprio 2

.Lds_early:
	s_and_b64 vcc, exec, s[36:37]
	s_cbranch_vccnz .LBB0_581
	s_and_b64 vcc, exec, s[56:57]
	s_cbranch_vccnz .Lsz_skip
	v_add_u32_e32 v34, 0xfffff000, v143
	v_add_u32_e32 v35, 0xfffff000, v145
	ds_read_b128 v[20:23], v34
	ds_read_b128 v[24:27], v35
	ds_read_b128 v[28:31], v225
	s_waitcnt lgkmcnt(1)
	v_sub_f16_e32 v8, v24, v20
	v_sub_f16_sdwa v9, v24, v20 dst_sel:DWORD dst_unused:UNUSED_PAD src0_sel:WORD_1 src1_sel:WORD_1
	v_sub_f16_e32 v11, v25, v21
	v_sub_f16_sdwa v24, v25, v21 dst_sel:DWORD dst_unused:UNUSED_PAD src0_sel:WORD_1 src1_sel:WORD_1
	v_sub_f16_e32 v32, v27, v23
	v_sub_f16_sdwa v27, v27, v23 dst_sel:DWORD dst_unused:UNUSED_PAD src0_sel:WORD_1 src1_sel:WORD_1
	v_sub_f16_e32 v25, v26, v22
	v_sub_f16_sdwa v26, v26, v22 dst_sel:DWORD dst_unused:UNUSED_PAD src0_sel:WORD_1 src1_sel:WORD_1
	v_pack_b32_f16 v27, v32, v27
	v_pack_b32_f16 v11, v11, v24
	s_waitcnt lgkmcnt(0)
	v_pk_fma_f16 v31, v31, v27, v23
	v_pack_b32_f16 v23, v25, v26
	v_pk_fma_f16 v11, v29, v11, v21
	v_pk_fma_f16 v27, v30, v23, v22
	v_fma_mix_f32 v23, v11, s87, 0 op_sel_hi:[1,0,0]
	v_cvt_f32_f16_e32 v22, v11
	v_exp_f32_e32 v24, v23
	v_fma_mix_f32 v23, v11, s87, 0 op_sel:[1,0,0] op_sel_hi:[1,0,0]
	v_pack_b32_f16 v8, v8, v9
	v_exp_f32_e32 v25, v23
	v_cvt_f32_f16_sdwa v23, v11 dst_sel:DWORD dst_unused:UNUSED_PAD src0_sel:WORD_1
	v_add_f32_e32 v11, 1.0, v24
	v_rcp_f32_e32 v24, v11
	v_add_f32_e32 v11, 1.0, v25
	v_rcp_f32_e32 v25, v11
	v_fma_mix_f32 v11, v27, s87, 0 op_sel_hi:[1,0,0]
	v_pk_fma_f16 v9, v28, v8, v20
	v_exp_f32_e32 v11, v11
	v_fma_mix_f32 v28, v27, s87, 0 op_sel:[1,0,0] op_sel_hi:[1,0,0]
	v_fma_mix_f32 v20, v9, s87, 0 op_sel_hi:[1,0,0]
	v_exp_f32_e32 v29, v28
	v_add_f32_e32 v11, 1.0, v11
	v_rcp_f32_e32 v28, v11
	v_fma_mix_f32 v21, v9, s87, 0 op_sel:[1,0,0] op_sel_hi:[1,0,0]
	v_add_f32_e32 v11, 1.0, v29
	v_rcp_f32_e32 v29, v11
	v_fma_mix_f32 v11, v31, s87, 0 op_sel_hi:[1,0,0]
	v_fma_mix_f32 v32, v31, s87, 0 op_sel:[1,0,0] op_sel_hi:[1,0,0]
	v_exp_f32_e32 v11, v11
	v_exp_f32_e32 v20, v20
	v_exp_f32_e32 v21, v21
	v_exp_f32_e32 v33, v32
	v_add_f32_e32 v11, 1.0, v11
	v_add_f32_e32 v20, 1.0, v20
	v_add_f32_e32 v21, 1.0, v21
	v_rcp_f32_e32 v32, v11
	v_add_f32_e32 v11, 1.0, v33
	v_cvt_f32_f16_e32 v8, v9
	v_cvt_f32_f16_sdwa v9, v9 dst_sel:DWORD dst_unused:UNUSED_PAD src0_sel:WORD_1
	v_rcp_f32_e32 v20, v20
	v_rcp_f32_e32 v21, v21
	v_cvt_f32_f16_e32 v26, v27
	v_cvt_f32_f16_sdwa v27, v27 dst_sel:DWORD dst_unused:UNUSED_PAD src0_sel:WORD_1
	v_cvt_f32_f16_e32 v30, v31
	v_cvt_f32_f16_sdwa v31, v31 dst_sel:DWORD dst_unused:UNUSED_PAD src0_sel:WORD_1
	v_rcp_f32_e32 v33, v11
	v_pk_fma_f32 v[8:9], v[8:9], v[20:21], 0 op_sel_hi:[1,1,0]
	v_pk_fma_f32 v[20:21], v[22:23], v[24:25], 0 op_sel_hi:[1,1,0]
	v_pk_fma_f32 v[24:25], v[26:27], v[28:29], 0 op_sel_hi:[1,1,0]
	v_pk_fma_f32 v[22:23], v[30:31], v[32:33], 0 op_sel_hi:[1,1,0]
	v_cvt_pk_f16_f32 v245, v20, v21
	v_cvt_pk_f16_f32 v247, v22, v23
	v_cvt_pk_f16_f32 v246, v24, v25
	v_cvt_pk_f16_f32 v244, v8, v9
.Lsz_skip:
	s_barrier
	s_and_saveexec_b64 s[24:25], s[22:23]
	s_cbranch_execz .Lds_e583
	ds_read_b128 v[20:23], v149 offset:56320
	ds_read_b128 v[24:27], v149 offset:56336
	ds_read2st64_b32 v[8:9], v150 offset1:1
	ds_read_b128 v[28:31], v151 offset:9216
	ds_read_b128 v[32:35], v152
	v_add_u32_e32 v87, 0x14800, v106
	ds_read_b128 v[36:39], v87 offset:2304
	ds_read_b128 v[40:43], v87 offset:2320
	ds_read_b128 v[82:85], v87 offset:2560
	ds_read_b128 v[158:161], v87 offset:2576
	s_waitcnt lgkmcnt(6)
	v_add_f32_e32 v11, 0, v20
	v_add_f32_e32 v8, v8, v9
	v_add_f32_e32 v9, v21, v11
	v_add_f32_e32 v9, v22, v9
	v_add_f32_e32 v9, v23, v9
	v_add_f32_e32 v9, v24, v9
	v_add_f32_e32 v9, v25, v9
	v_add_f32_e32 v9, v26, v9
	v_add_f32_e32 v9, v27, v9
	s_waitcnt lgkmcnt(4)
	v_cvt_f32_f16_e32 v164, v28
	v_cvt_f32_f16_sdwa v165, v28 dst_sel:DWORD dst_unused:UNUSED_PAD src0_sel:WORD_1
	v_add_f32_dpp v9, v9, v9 quad_perm:[1,0,3,2] row_mask:0xf bank_mask:0xf bound_ctrl:1
	v_cvt_f32_f16_e32 v28, v29
	v_cvt_f32_f16_sdwa v29, v29 dst_sel:DWORD dst_unused:UNUSED_PAD src0_sel:WORD_1
	v_add_f32_dpp v9, v9, v9 quad_perm:[2,3,0,1] row_mask:0xf bank_mask:0xf bound_ctrl:1
	v_cvt_f32_f16_e32 v166, v32
	v_cvt_f32_f16_sdwa v167, v32 dst_sel:DWORD dst_unused:UNUSED_PAD src0_sel:WORD_1
	v_add_f32_dpp v9, v9, v9 row_half_mirror row_mask:0xf bank_mask:0xf bound_ctrl:1
	v_mul_f32_e32 v86, 0x3c800000, v9
	v_pk_add_f32 v[20:21], v[20:21], v[86:87] op_sel_hi:[1,0] neg_lo:[0,1] neg_hi:[0,1]
	v_pk_mul_f32 v[162:163], v[20:21], v[20:21]
	v_pk_add_f32 v[22:23], v[22:23], v[86:87] op_sel_hi:[1,0] neg_lo:[0,1] neg_hi:[0,1]
	v_pk_mul_f32 v[168:169], v[22:23], v[22:23]
	v_add_f32_e32 v9, v162, v163
	v_pk_add_f32 v[24:25], v[24:25], v[86:87] op_sel_hi:[1,0] neg_lo:[0,1] neg_hi:[0,1]
	v_add_f32_e32 v9, v168, v9
	v_pk_mul_f32 v[170:171], v[24:25], v[24:25]
	v_add_f32_e32 v9, v169, v9
	v_pk_add_f32 v[26:27], v[26:27], v[86:87] op_sel_hi:[1,0] neg_lo:[0,1] neg_hi:[0,1]
	v_add_f32_e32 v9, v170, v9
	v_pk_mul_f32 v[86:87], v[26:27], v[26:27]
	v_add_f32_e32 v9, v171, v9
	v_add_f32_e32 v9, v86, v9
	v_add_f32_e32 v9, v87, v9
	v_cvt_f32_f16_e32 v32, v33
	v_cvt_f32_f16_sdwa v33, v33 dst_sel:DWORD dst_unused:UNUSED_PAD src0_sel:WORD_1
	v_add_f32_dpp v9, v9, v9 quad_perm:[1,0,3,2] row_mask:0xf bank_mask:0xf bound_ctrl:1
	v_cvt_f32_f16_e32 v172, v30
	v_cvt_f32_f16_sdwa v173, v30 dst_sel:DWORD dst_unused:UNUSED_PAD src0_sel:WORD_1
	v_add_f32_dpp v9, v9, v9 quad_perm:[2,3,0,1] row_mask:0xf bank_mask:0xf bound_ctrl:1
	v_cvt_f32_f16_e32 v162, v34
	v_cvt_f32_f16_sdwa v163, v34 dst_sel:DWORD dst_unused:UNUSED_PAD src0_sel:WORD_1
	v_add_f32_dpp v9, v9, v9 row_half_mirror row_mask:0xf bank_mask:0xf bound_ctrl:1
	v_fmamk_f32 v9, v9, 0x3c800000, v153
	v_rsq_f32_e32 v86, v9
	s_nop 0
	v_pk_mul_f32 v[20:21], v[20:21], v[86:87] op_sel_hi:[1,0]
	v_pk_mul_f32 v[22:23], v[22:23], v[86:87] op_sel_hi:[1,0]
	s_waitcnt lgkmcnt(0)
	v_pk_fma_f32 v[20:21], v[36:37], v[20:21], v[82:83]
	v_pk_fma_f32 v[22:23], v[38:39], v[22:23], v[84:85]
	v_pk_fma_f32 v[20:21], v[8:9], v[164:165], v[20:21] op_sel_hi:[0,1,1]
	v_pk_fma_f32 v[22:23], v[8:9], v[28:29], v[22:23] op_sel_hi:[0,1,1]
	v_pk_mul_f32 v[20:21], v[20:21], v[166:167]
	v_pk_mul_f32 v[22:23], v[22:23], v[32:33]
	v_cvt_pk_f16_f32 v20, v20, v21
	v_cvt_pk_f16_f32 v21, v22, v23
	v_pk_mul_f32 v[22:23], v[24:25], v[86:87] op_sel_hi:[1,0]
	v_cvt_f32_f16_e32 v24, v31
	v_cvt_f32_f16_sdwa v25, v31 dst_sel:DWORD dst_unused:UNUSED_PAD src0_sel:WORD_1
	v_cvt_f32_f16_e32 v28, v35
	v_cvt_f32_f16_sdwa v29, v35 dst_sel:DWORD dst_unused:UNUSED_PAD src0_sel:WORD_1
	v_pk_mul_f32 v[26:27], v[26:27], v[86:87] op_sel_hi:[1,0]
	v_pk_fma_f32 v[22:23], v[40:41], v[22:23], v[158:159]
	v_pk_fma_f32 v[26:27], v[42:43], v[26:27], v[160:161]
	v_pk_fma_f32 v[22:23], v[8:9], v[172:173], v[22:23] op_sel_hi:[0,1,1]
	v_pk_fma_f32 v[8:9], v[8:9], v[24:25], v[26:27] op_sel_hi:[0,1,1]
	v_pk_mul_f32 v[22:23], v[22:23], v[162:163]
	v_pk_mul_f32 v[8:9], v[8:9], v[28:29]
	v_cvt_pk_f16_f32 v22, v22, v23
	v_cvt_pk_f16_f32 v23, v8, v9
	v_add_u32_e32 v8, s29, v107
	v_ashrrev_i32_e32 v9, 31, v8
	v_lshlrev_b64 v[8:9], 11, v[8:9]
	v_lshl_add_u64 v[8:9], v[60:61], 0, v[8:9]
	global_store_dwordx4 v[8:9], v[20:23], off sc1
	s_nop 1
.Lds_e583:
	s_or_b64 exec, exec, s[24:25]
	s_and_b64 vcc, exec, s[56:57]
	s_cbranch_vccnz .Lsz_skip2
	v_add_u32_e32 v36, 0xfffff000, v146
	ds_write_b128 v36, v[244:247]
.Lsz_skip2:
	s_waitcnt vmcnt(1)
	s_waitcnt lgkmcnt(0)
	s_barrier
	s_branch .Lds_after
